# all phases XCD-owned; grid barriers only into phases 1/6/9/14, XCD-group barriers elsewhere; small start stagger
# speedup vs baseline: 1.0054x; 1.0054x over previous
; DI bool sb_tile(int bid, int nb, int it, int NT, int& mt, int& nt) {
;   const int G = nb >> 3, x = bid & 7, l = bid >> 3;
;   const int s = l + it * G;
;   const int sb = (s >> 5) * 8 + x, w = s & 31;
;   if (NT == 4) {
;     if (sb >= 48) return false;
;     mt = sb * 8 + (w >> 2); nt = w & 3;
;     return true;
;   }
;   const int NG = NT >> 1;
;   if (sb >= 24 * NG) return false;
;   const int mg = sb / NG, ng = sb - mg * NG;
;   mt = mg * 16 + (w >> 1); nt = ng * 2 + (w & 1);
;   return true;
; }
; __global__ void __launch_bounds__(NTHR, 2) mega(Params p, int ph_lo, int ph_hi) {
;   __shared__ __attribute__((aligned(16))) char smem[SMEM_BYTES];
;   cg::grid_group grid = cg::this_grid();
;   for (int ph = ph_lo; ph < ph_hi; ++ph) {
;     if (ph > ph_lo) grid.sync();
;     run_phase(p, ph, smem);
_Z4mega6Paramsii:
	s_load_dwordx2 s[30:31], s[0:1], 0xa8
	s_waitcnt lgkmcnt(0)
	s_cmp_ge_i32 s30, s31
	s_cbranch_scc1 .LBB0_411
	s_load_dwordx16 s[4:19], s[0:1], 0x0
	s_load_dwordx16 s[36:51], s[0:1], 0x40
	s_load_dwordx2 s[88:89], s[0:1], 0xa0
	s_load_dwordx8 s[20:27], s[0:1], 0x80
	s_load_dword s34, s[0:1], 0xb0
	s_mov_b32 s28, s2
	s_add_u32 s2, s0, 0xb0
	s_addc_u32 s3, s1, 0
	s_mov_b32 s1, 0
	v_writelane_b32 v253, s2, 0
	s_waitcnt lgkmcnt(0)
	s_ashr_i32 s35, s34, 31
	s_cmp_lg_u64 s[34:35], 0x100
	v_writelane_b32 v253, s3, 1
	s_cselect_b64 s[52:53], -1, 0
	v_and_b32_e32 v194, 0x3ff, v0
	v_and_b32_e32 v0, 0x3fffffff, v0
	v_writelane_b32 v253, s0, 2
	s_add_u32 s54, s88, 0x304a000
	s_addc_u32 s55, s89, 0
	v_writelane_b32 v253, s1, 3
	v_cmp_eq_u32_e64 s[0:1], 0, v0
	s_cmpk_lt_i32 s28, 0xc00
	v_mbcnt_lo_u32_b32 v0, -1, 0
	v_writelane_b32 v253, s0, 4
	v_mbcnt_hi_u32_b32 v196, -1, v0
	v_and_b32_e32 v0, 64, v196
	v_writelane_b32 v253, s1, 5
	s_cselect_b64 s[0:1], -1, 0
	v_writelane_b32 v253, s0, 6
	s_cmpk_lt_i32 s28, 0x80
	s_mov_b64 s[94:95], 0x100
	v_writelane_b32 v253, s1, 7
	s_cselect_b64 s[0:1], -1, 0
	s_add_u32 s56, s88, 0x2fca000
	s_addc_u32 s57, s89, 0
	v_writelane_b32 v253, s0, 8
	s_cmpk_lt_i32 s28, 0x17f4
	v_mov_b32_e32 v1, 0
	v_writelane_b32 v253, s1, 9
	s_cselect_b64 s[0:1], -1, 0
	v_writelane_b32 v253, s0, 10
	s_cmp_lg_u64 s[48:49], 0
	s_cselect_b64 s[58:59], -1, 0
	v_writelane_b32 v253, s1, 11
	s_cmp_lg_u64 s[44:45], 0
	s_cselect_b64 s[60:61], -1, 0
	s_cmp_lg_u64 s[40:41], 0
	v_writelane_b32 v253, s36, 12
	s_cselect_b64 s[62:63], -1, 0
	s_cmp_lg_u64 s[36:37], 0
	v_writelane_b32 v253, s37, 13
	v_writelane_b32 v253, s38, 14
	v_writelane_b32 v253, s39, 15
	v_writelane_b32 v253, s40, 16
	v_writelane_b32 v253, s41, 17
	v_writelane_b32 v253, s42, 18
	v_writelane_b32 v253, s43, 19
	v_writelane_b32 v253, s44, 20
	v_writelane_b32 v253, s45, 21
	v_writelane_b32 v253, s46, 22
	v_writelane_b32 v253, s47, 23
	v_writelane_b32 v253, s48, 24
	v_writelane_b32 v253, s49, 25
	v_writelane_b32 v253, s50, 26
	v_writelane_b32 v253, s51, 27
	v_writelane_b32 v253, s4, 28
	s_cselect_b64 s[64:65], -1, 0
	s_cmp_lg_u64 s[10:11], 0
	v_writelane_b32 v253, s5, 29
	v_writelane_b32 v253, s6, 30
	v_writelane_b32 v253, s7, 31
	v_writelane_b32 v253, s8, 32
	v_writelane_b32 v253, s9, 33
	v_writelane_b32 v253, s10, 34
	v_writelane_b32 v253, s11, 35
	v_writelane_b32 v253, s12, 36
	s_cselect_b64 s[66:67], -1, 0
	s_add_u32 s68, s88, 0x2fc0000
	v_writelane_b32 v253, s13, 37
	s_addc_u32 s69, s89, 0
	v_writelane_b32 v253, s14, 38
	s_add_u32 s70, s88, 0xf04a000
	v_writelane_b32 v253, s15, 39
	s_addc_u32 s71, s89, 0
	s_ashr_i32 s0, s28, 5
	v_writelane_b32 v253, s16, 40
	s_and_b32 s72, s28, 7
	s_and_b32 s0, s0, -8
	v_writelane_b32 v253, s17, 41
	s_ashr_i32 s73, s28, 3
	s_or_b32 s2, s0, s72
	s_mul_i32 s2, s72, 6
	v_writelane_b32 v253, s18, 42
	s_cmp_lt_i32 s2, 48
	v_writelane_b32 v253, s19, 43
	s_cselect_b64 s[0:1], -1, 0
	v_writelane_b32 v253, s0, 44
	s_and_b32 s15, s73, 3
	s_mov_b32 s86, 0x358637bd
	v_writelane_b32 v253, s1, 45
	s_lshl_b32 s0, s2, 3
	s_bfe_u32 s1, s73, 0x30002
	s_or_b32 s0, s0, s1
	s_lshl_b32 s4, s0, 8
	s_ashr_i32 s5, s4, 31
	v_writelane_b32 v253, s0, 46
	s_mul_i32 s0, s0, 0x160000
	s_mul_hi_i32 s3, s4, 0x1600
	s_add_u32 s6, s70, s0
	s_addc_u32 s7, s71, s3
	v_writelane_b32 v253, s6, 47
	s_mul_i32 s1, s15, 0xb0000
	s_movk_i32 s87, 0x90
	v_writelane_b32 v253, s7, 48
	s_or_b32 s6, s4, 0x80
	s_ashr_i32 s7, s6, 31
	s_mul_i32 s3, s6, 0x1600
	s_mul_hi_i32 s0, s6, 0x1600
	s_add_u32 s8, s70, s3
	s_addc_u32 s9, s71, s0
	s_ashr_i32 s74, s34, 3
	v_writelane_b32 v253, s8, 49
	s_mul_i32 s2, s72, 37
	s_cmpk_lt_i32 s2, 0x108
	s_mul_hi_i32 s0, s2, 0x2e8ba2e9
	v_writelane_b32 v253, s9, 50
	s_cselect_b64 s[8:9], -1, 0
	s_lshr_b32 s3, s0, 31
	s_ashr_i32 s0, s0, 1
	s_add_i32 s0, s0, s3
	s_mul_i32 s3, s0, -11
	v_writelane_b32 v253, s8, 51
	s_add_i32 s3, s3, s2
	s_lshl_b32 s0, s0, 4
	s_bfe_u32 s14, s73, 0x40001
	v_writelane_b32 v253, s9, 52
	s_or_b32 s8, s0, s14
	s_lshl_b32 s0, s3, 1
	s_and_b32 s3, s73, 1
	s_or_b32 s0, s0, s3
	s_lshl_b32 s10, s0, 8
	v_writelane_b32 v253, s8, 53
	s_ashr_i32 s11, s10, 31
	s_lshl_b32 s8, s8, 8
	v_writelane_b32 v253, s0, 54
	s_lshl_b64 s[12:13], s[10:11], 11
	v_writelane_b32 v253, s12, 55
	s_ashr_i32 s9, s8, 31
	s_mov_b64 s[78:79], 0x304a100
	v_writelane_b32 v253, s13, 56
	s_lshl_b64 s[12:13], s[8:9], 11
	s_add_u32 s12, s54, s12
	s_addc_u32 s13, s55, s13
	s_bitset1_b32 s10, 7
	s_bitset1_b32 s8, 7
	s_ashr_i32 s11, s10, 31
	s_ashr_i32 s9, s8, 31
	s_lshl_b64 s[10:11], s[10:11], 11
	s_lshl_b64 s[8:9], s[8:9], 11
	s_add_u32 s8, s54, s8
	s_addc_u32 s9, s55, s9
	s_lshl_b32 s0, s15, 18
	s_lshl_b64 s[4:5], s[4:5], 11
	s_add_u32 s4, s54, s4
	s_addc_u32 s5, s55, s5
	v_writelane_b32 v254, s4, 0
	v_writelane_b32 v253, s12, 57
	s_mov_b64 s[96:97], 0x308a100
	v_writelane_b32 v254, s5, 1
	s_lshl_b64 s[4:5], s[6:7], 11
	s_add_u32 s4, s54, s4
	s_addc_u32 s5, s55, s5
	v_writelane_b32 v254, s4, 2
	v_writelane_b32 v253, s13, 58
	v_writelane_b32 v253, s10, 59
	v_writelane_b32 v254, s5, 3
	s_add_u32 s4, s88, 0x37e4a000
	s_addc_u32 s5, s89, 0
	v_writelane_b32 v254, s4, 4
	s_lshr_b32 s75, s28, 3
	v_writelane_b32 v253, s11, 60
	v_writelane_b32 v254, s5, 5
	s_lshl_b32 s4, s28, 1
	s_and_b32 s4, s4, 14
	s_ashr_i32 s5, s28, 7
	s_add_i32 s76, s4, s5
	s_add_u32 s77, s88, 0x2be4a000
	s_addc_u32 s81, s89, 0
	s_add_u32 s82, s88, 0x3064a000
	s_addc_u32 s83, s89, 0
	s_add_u32 s92, s88, 0x34e4a000
	s_addc_u32 s4, s89, 0
	v_writelane_b32 v254, s4, 6
	s_add_u32 s4, s88, 0x37e4a030
	s_addc_u32 s5, s89, 0
	v_writelane_b32 v254, s4, 7
	v_writelane_b32 v253, s8, 61
	s_mov_b64 s[90:91], 0x304a180
; DI bool sb_tile(int bid, int nb, int it, int NT, int& mt, int& nt) {
;   const int G = nb >> 3, x = bid & 7, l = bid >> 3;
;   const int s = l + it * G;
;   const int sb = (s >> 5) * 8 + x, w = s & 31;
;   if (NT == 4) {
;     if (sb >= 48) return false;
;     mt = sb * 8 + (w >> 2); nt = w & 3;
;     return true;
;   }
;   const int NG = NT >> 1;
;   if (sb >= 24 * NG) return false;
;   const int mg = sb / NG, ng = sb - mg * NG;
;   mt = mg * 16 + (w >> 1); nt = ng * 2 + (w & 1);
;   return true;
; }
; template <int EPI, bool GSCALE = false>
; DI void gemm8_phase(const Params& p, int layer, const u16* A, const u16* Bt, int K, int NT, char* smem) {
;   const int bid = blockIdx.x, nb = gridDim.x;
;   int mt, nt;
;   bool have = sb_tile(bid, nb, 0, NT, mt, nt);
;   if (have) gemm8_prestage(A, Bt, K, mt * 256, nt * 256, smem);
	v_writelane_b32 v254, s5, 8
	s_add_u32 s4, s88, 0xf04a600
	v_writelane_b32 v254, s4, 9
	s_addc_u32 s4, s89, 0
	v_writelane_b32 v254, s4, 10
	s_add_u32 s4, s88, 0xf04a900
	v_writelane_b32 v254, s4, 11
	s_addc_u32 s4, s89, 0
	v_writelane_b32 v254, s4, 12
	s_add_u32 s4, s88, 0xf04a800
	v_writelane_b32 v254, s4, 13
	s_addc_u32 s4, s89, 0
	v_writelane_b32 v254, s4, 14
	s_add_u32 s4, s88, 0x37e4a010
	s_addc_u32 s5, s89, 0
	v_writelane_b32 v254, s4, 15
	v_writelane_b32 v253, s9, 62
	v_writelane_b32 v253, s15, 63
	v_writelane_b32 v254, s5, 16
	s_add_u32 s4, s88, 0xf04a200
	v_writelane_b32 v254, s4, 17
	s_addc_u32 s4, s89, 0
	v_writelane_b32 v254, s4, 18
	s_add_u32 s4, s88, 0xf04a400
	v_writelane_b32 v254, s4, 19
	s_addc_u32 s4, s89, 0
	v_writelane_b32 v254, s4, 20
	s_add_u32 s4, s88, 0xf04aa00
	v_writelane_b32 v254, s4, 21
	s_addc_u32 s4, s89, 0
	v_writelane_b32 v254, s4, 22
	s_add_u32 s4, s88, 0xf04ac00
	v_writelane_b32 v254, s4, 23
	s_addc_u32 s4, s89, 0
	v_writelane_b32 v254, s4, 24
	s_add_u32 s4, s88, 0xf04ae00
	v_writelane_b32 v254, s4, 25
	s_addc_u32 s4, s89, 0
	v_writelane_b32 v254, s4, 26
	s_add_u32 s4, s88, 0x37e4a020
	s_addc_u32 s5, s89, 0
	v_writelane_b32 v254, s4, 27
	s_cmpk_lt_i32 s28, 0x600
	s_mov_b32 s33, 0xefa18f08
	v_writelane_b32 v254, s5, 28
	s_cselect_b64 s[4:5], -1, 0
	v_writelane_b32 v254, s4, 29
	s_cmpk_lt_i32 s28, 0x300
	s_mov_b32 s80, 0x41000000
	v_writelane_b32 v254, s5, 30
	s_cselect_b64 s[4:5], -1, 0
	v_writelane_b32 v254, s4, 31
	v_add_u32_e32 v197, 64, v0
	v_xor_b32_e32 v252, 1, v196
	v_writelane_b32 v254, s5, 32
	s_add_u32 s4, s88, 0xf04b000
	s_addc_u32 s5, s89, 0
	v_writelane_b32 v254, s4, 33
	v_xor_b32_e32 v195, 2, v196
	v_xor_b32_e32 v198, 4, v196
	v_writelane_b32 v254, s5, 34
	s_add_u32 s4, s88, 0xf04b200
	s_addc_u32 s5, s89, 0
	v_writelane_b32 v254, s4, 35
	s_mul_i32 s2, s72, 17
	s_cmpk_lt_i32 s2, 0x78
	v_xor_b32_e32 v199, 8, v196
	v_writelane_b32 v254, s5, 36
	s_cselect_b64 s[4:5], -1, 0
	v_writelane_b32 v254, s4, 37
	v_xor_b32_e32 v200, 16, v196
	v_xor_b32_e32 v201, 32, v196
	v_writelane_b32 v254, s5, 38
	s_mul_hi_i32 s4, s2, 0x66666667
	s_lshr_b32 s5, s4, 31
	s_ashr_i32 s4, s4, 1
	s_add_i32 s4, s4, s5
	s_mul_i32 s5, s4, -5
	s_add_i32 s5, s5, s2
	s_lshl_b32 s2, s4, 4
	s_or_b32 s4, s2, s14
	s_lshl_b32 s2, s5, 1
	s_or_b32 s3, s2, s3
	v_writelane_b32 v254, s4, 39
	s_lshl_b32 s2, s4, 8
	s_lshl_b32 s4, s3, 8
	s_ashr_i32 s5, s4, 31
	v_writelane_b32 v254, s3, 40
	s_lshl_b64 s[6:7], s[4:5], 11
	v_writelane_b32 v254, s6, 41
	s_ashr_i32 s3, s2, 31
	s_mov_b64 s[12:13], s[20:21]
	v_writelane_b32 v254, s7, 42
	s_lshl_b64 s[6:7], s[2:3], 11
	s_add_u32 s6, s54, s6
	s_addc_u32 s7, s55, s7
	s_bitset1_b32 s4, 7
	s_bitset1_b32 s2, 7
	v_writelane_b32 v254, s6, 43
	s_ashr_i32 s5, s4, 31
	s_ashr_i32 s3, s2, 31
	v_writelane_b32 v254, s7, 44
	s_lshl_b64 s[4:5], s[4:5], 11
	s_lshl_b64 s[2:3], s[2:3], 11
	v_writelane_b32 v254, s4, 45
	s_add_u32 s2, s54, s2
	s_addc_u32 s3, s55, s3
	v_writelane_b32 v254, s5, 46
	v_writelane_b32 v254, s2, 47
	s_ashr_i32 s29, s28, 31
	s_mov_b64 s[18:19], s[26:27]
	v_writelane_b32 v254, s3, 48
	s_lshl_b64 s[2:3], s[28:29], 17
	s_add_u32 s2, s18, s2
	s_addc_u32 s3, s19, s3
	v_writelane_b32 v254, s2, 49
	s_lshl_b32 s0, s0, 1
	s_mov_b64 s[14:15], s[22:23]
	v_writelane_b32 v254, s3, 50
	s_lshl_b64 s[2:3], s[34:35], 17
	s_mov_b64 s[16:17], s[24:25]
	v_writelane_b32 v254, s2, 51
	v_writelane_b32 v255, s0, 0
	v_writelane_b32 v255, s12, 1
	v_writelane_b32 v254, s3, 52
	s_lshl_b32 s2, s28, 9
	v_writelane_b32 v254, s2, 53
	s_lshl_b32 s2, s34, 9
	v_writelane_b32 v255, s13, 2
	v_writelane_b32 v254, s2, 54
	s_lshl_b64 s[2:3], s[28:29], 5
	v_writelane_b32 v255, s14, 3
	v_writelane_b32 v254, s2, 55
	v_writelane_b32 v255, s15, 4
	v_writelane_b32 v255, s16, 5
	v_writelane_b32 v254, s3, 56
	s_lshl_b64 s[2:3], s[34:35], 5
	v_writelane_b32 v254, s2, 57
	v_writelane_b32 v255, s17, 6
	v_writelane_b32 v255, s18, 7
	v_writelane_b32 v254, s3, 58
	s_lshl_b32 s2, s28, 8
	v_writelane_b32 v254, s2, 59
	s_lshl_b32 s2, s34, 8
	v_writelane_b32 v255, s19, 8
	v_writelane_b32 v254, s2, 60
	s_lshl_b32 s2, s28, 7
	v_writelane_b32 v255, s28, 9
	s_mov_b32 s4, s30
	v_writelane_b32 v254, s2, 61
	v_writelane_b32 v255, s29, 10
	v_writelane_b32 v255, s30, 11
	s_lshl_b32 s2, s34, 7
	v_writelane_b32 v254, s2, 62
	v_writelane_b32 v255, s31, 12
	v_writelane_b32 v255, s34, 13
	s_lshl_b32 s1, s1, 1
	v_writelane_b32 v254, s1, 63
	v_writelane_b32 v255, s35, 14
	v_writelane_b32 v255, s52, 15
	s_mov_b64 s[2:3], 0x308a080
	v_mov_b32_e32 v206, 0xf149f2ca
	v_writelane_b32 v255, s53, 16
	v_writelane_b32 v255, s54, 17
	v_mov_b32_e32 v202, 0x3e38aa3b
	s_nop 0
	v_writelane_b32 v255, s55, 18
	v_writelane_b32 v255, s56, 19
	s_nop 1
	v_writelane_b32 v255, s57, 20
	v_writelane_b32 v255, s58, 21
	s_nop 1
	v_writelane_b32 v255, s59, 22
	v_writelane_b32 v255, s60, 23
	s_nop 1
	v_writelane_b32 v255, s61, 24
	v_writelane_b32 v255, s62, 25
	s_nop 1
	v_writelane_b32 v255, s63, 26
	v_writelane_b32 v255, s64, 27
	s_nop 1
	v_writelane_b32 v255, s65, 28
	v_writelane_b32 v255, s66, 29
	s_nop 1
	v_writelane_b32 v255, s67, 30
	v_writelane_b32 v255, s68, 31
	s_nop 1
	v_writelane_b32 v255, s69, 32
	v_writelane_b32 v255, s70, 33
	s_nop 1
	v_writelane_b32 v255, s71, 34
	v_writelane_b32 v255, s72, 35
	v_writelane_b32 v255, s73, 36
	v_writelane_b32 v255, s74, 37
	v_writelane_b32 v255, s75, 38
	v_writelane_b32 v255, s76, 39
	v_writelane_b32 v255, s77, 40
	v_writelane_b32 v255, s81, 41
	v_writelane_b32 v255, s82, 42
	v_writelane_b32 v255, s83, 43
	v_writelane_b32 v255, s92, 44
	s_mov_b32 s5, 0
	v_writelane_b32 v255, s5, 60
	v_writelane_b32 v255, s5, 61
	v_writelane_b32 v255, s5, 59
	v_writelane_b32 v255, s5, 62
	v_readfirstlane_b32 s32, v194
	s_nop 3
	s_lshr_b32 s32, s32, 8
	s_branch .LBB0_3

; __global__ void __launch_bounds__(NTHR, 2) mega(Params p, int ph_lo, int ph_hi) {
;     ...
;   cg::grid_group grid = cg::this_grid();
;   for (int ph = ph_lo; ph < ph_hi; ++ph) {
;     if (ph > ph_lo) grid.sync();
;     run_phase(p, ph, smem);
.LBB0_3:
	s_cmp_le_i32 s4, s30
	s_mov_b32 s12, 0x3a800000
	v_writelane_b32 v255, s4, 45
	s_cbranch_scc1 .LBB0_15
	s_sub_i32 s0, s4, s30
	s_cmp_lt_i32 s0, 2
	s_cbranch_scc1 .Lcg_sync
	s_waitcnt vmcnt(0) lgkmcnt(0)
	s_barrier
	s_mov_b64 s[0:1], exec
	v_readlane_b32 s6, v253, 4
	v_readlane_b32 s7, v253, 5
	s_and_b64 s[6:7], s[0:1], s[6:7]
	s_mov_b64 exec, s[6:7]
	s_cbranch_execz .Lfb_done
	buffer_wbl2 sc1
	s_sub_i32 s8, s4, s30
	v_readlane_b32 s9, v255, 13
	s_mov_b32 s10, 0x1bdbc
	s_lshr_b32 s10, s10, s8
	s_and_b32 s11, s10, 1
	s_cmp_lt_i32 s8, 10
	s_cbranch_scc0 .Lfb_usey
	s_cmp_eq_u32 s11, 0
	s_cbranch_scc0 .Lfb_xl
	v_readlane_b32 s8, v255, 61
	s_add_i32 s8, s8, 1
	s_mov_b32 s10, 0x1cc2000
	v_writelane_b32 v255, s8, 61
	s_branch .Lfb_go

; DI void run_phase(const Params& p, int ph, char* smem) {
;     ...
;   const int layer = (ph - 1) >> 3, sub = (ph - 1) & 7;
;   const u16* wl = wtb + (size_t)layer * WT_LAYER;
;   switch (sub) {
.LBB0_15:
	s_add_i32 s5, s4, -1
	s_cmp_gt_u32 s5, 14
	s_cbranch_scc1 .Lstg_done
	s_and_b32 s5, s5, 7
	s_mov_b32 s6, 0
	s_cmp_eq_u32 s5, 0
	s_cselect_b32 s6, 8, s6
	s_cmp_eq_u32 s5, 3
	s_cselect_b32 s6, 0, s6
	s_cmp_eq_u32 s5, 5
	s_cselect_b32 s6, 8, s6
	s_cmp_eq_u32 s5, 6
	s_cselect_b32 s6, 0, s6
	s_and_b32 s7, s28, 7
	s_mul_i32 s6, s6, s7
	s_cmp_eq_u32 s6, 0
	s_cbranch_scc1 .Lstg_done

; DI bool att_tile_index(int bid, int nb, int it, int& tile) {
;   if (nb != 256) { tile = bid + it * nb; return tile < 1536; }
;   const int x = bid & 7, l = bid >> 3;
;   const int pair = 2 * (it * 8 + x) + (l >> 4);
;   tile = pair * 16 + ((l + 3 * it) & 15);
;   return pair < 96;
; }
.LBB0_107:
	s_lshl_b32 s0, s18, 1
	s_mul_i32 s4, s18, 3
	s_add_i32 s0, s0, s76
	s_add_i32 s4, s4, s75
	s_lshr_b32 s1, s76, 1
	s_mul_i32 s1, s1, 10
	s_add_i32 s0, s0, s1
	s_lshl_b32 s1, s0, 4
	s_and_b32 s4, s4, 15
	s_or_b32 s6, s1, s4
	s_cmpk_lt_i32 s18, 6
	s_cselect_b64 s[0:1], -1, 0
	s_mov_b64 s[4:5], -1
	s_and_b64 vcc, exec, s[0:1]
	s_cbranch_vccz .LBB0_102

; DI bool att_tile_index(int bid, int nb, int it, int& tile) {
;   if (nb != 256) { tile = bid + it * nb; return tile < 1536; }
;   const int x = bid & 7, l = bid >> 3;
;   const int pair = 2 * (it * 8 + x) + (l >> 4);
;   tile = pair * 16 + ((l + 3 * it) & 15);
;   return pair < 96;
; }
.LBB0_138:
	s_lshl_b32 s0, s16, 1
	s_mul_i32 s4, s16, 3
	s_add_i32 s0, s0, s76
	s_add_i32 s4, s4, s75
	s_lshr_b32 s1, s76, 1
	s_mul_i32 s1, s1, 10
	s_add_i32 s0, s0, s1
	s_lshl_b32 s1, s0, 4
	s_and_b32 s4, s4, 15
	s_or_b32 s6, s1, s4
	s_cmpk_lt_i32 s16, 6
	s_cselect_b64 s[0:1], -1, 0
	s_mov_b64 s[4:5], -1
	s_and_b64 vcc, exec, s[0:1]
	s_cbranch_vccz .LBB0_133

; DI bool att_tile_index(int bid, int nb, int it, int& tile) {
;   if (nb != 256) { tile = bid + it * nb; return tile < 1536; }
;   const int x = bid & 7, l = bid >> 3;
;   const int pair = 2 * (it * 8 + x) + (l >> 4);
;   tile = pair * 16 + ((l + 3 * it) & 15);
;   return pair < 96;
; }
.LBB0_163:
	s_lshl_b32 s0, s16, 1
	s_mul_i32 s4, s16, 3
	s_add_i32 s0, s0, s76
	s_add_i32 s4, s4, s75
	s_lshr_b32 s1, s76, 1
	s_mul_i32 s1, s1, 10
	s_add_i32 s0, s0, s1
	s_lshl_b32 s1, s0, 4
	s_and_b32 s4, s4, 15
	s_or_b32 s10, s1, s4
	s_cmpk_lt_i32 s16, 6
	s_cselect_b64 s[0:1], -1, 0
	s_mov_b64 s[4:5], -1
	s_and_b64 vcc, exec, s[0:1]
	s_cbranch_vccz .LBB0_158

; DI bool att_tile_index(int bid, int nb, int it, int& tile) {
;   if (nb != 256) { tile = bid + it * nb; return tile < 1536; }
;   const int x = bid & 7, l = bid >> 3;
;   const int pair = 2 * (it * 8 + x) + (l >> 4);
;   tile = pair * 16 + ((l + 3 * it) & 15);
;   return pair < 96;
; }
.LBB0_198:
	s_lshl_b32 s0, s29, 1
	s_mul_i32 s4, s29, 3
	s_add_i32 s0, s0, s76
	s_add_i32 s4, s4, s75
	s_lshr_b32 s1, s76, 1
	s_mul_i32 s1, s1, 10
	s_add_i32 s0, s0, s1
	s_lshl_b32 s1, s0, 4
	s_and_b32 s4, s4, 15
	s_or_b32 s10, s1, s4
	s_cmpk_lt_i32 s29, 6
	s_cselect_b64 s[0:1], -1, 0
	s_andn2_b64 vcc, exec, s[0:1]
	s_mov_b64 s[0:1], -1
	s_cbranch_vccnz .LBB0_193

; DI bool sb_tile(int bid, int nb, int it, int NT, int& mt, int& nt) {
;   const int G = nb >> 3, x = bid & 7, l = bid >> 3;
;   const int s = l + it * G;
;   const int sb = (s >> 5) * 8 + x, w = s & 31;
;   if (NT == 4) {
;     if (sb >= 48) return false;
;     mt = sb * 8 + (w >> 2); nt = w & 3;
;     return true;
;   }
;   const int NG = NT >> 1;
;   if (sb >= 24 * NG) return false;
;   const int mg = sb / NG, ng = sb - mg * NG;
;   mt = mg * 16 + (w >> 1); nt = ng * 2 + (w & 1);
;   return true;
; }
; template <int EPI, bool GSCALE = false>
; DI void gemm8_phase(const Params& p, int layer, const u16* A, const u16* Bt, int K, int NT, char* smem) {
;     ...
;   for (int it = 0; have; ++it) {
;     int mt2 = 0, nt2 = 0;
;     const bool have2 = sb_tile(bid, nb, it + 1, NT, mt2, nt2);
;     gemm8_tile<EPI, GSCALE>(p, layer, A, Bt, K, mt * 256, nt * 256, smem, have2, mt2 * 256, nt2 * 256);
;     have = have2; mt = mt2; nt = nt2;
;   }
.LBB0_236:
	s_add_i32 s12, s12, 1
	s_mul_i32 s0, s12, s74
	s_add_i32 s0, s0, s73
	s_ashr_i32 s8, s0, 5
	s_lshl_b32 s10, s72, 1
	s_add_i32 s10, s10, s8
	s_cmpk_gt_i32 s10, 14
	s_cselect_b32 s11, 15, 0
	s_sub_i32 s10, s10, s11
	s_mul_i32 s1, s72, 15
	s_add_i32 s1, s1, s10
	s_cmpk_lt_i32 s8, 15
	s_cselect_b64 s[10:11], -1, 0
	s_cmpk_gt_i32 s8, 14
	s_cselect_b64 s[8:9], -1, 0
	s_and_b64 vcc, exec, s[8:9]
	s_mov_b32 s13, 0
	s_mov_b32 s14, 0
	s_cbranch_vccnz .LBB0_238
	s_mul_hi_i32 s6, s1, 0x66666667
	s_lshr_b32 s7, s6, 31
	s_ashr_i32 s6, s6, 1
	s_add_i32 s6, s6, s7
	s_mul_i32 s7, s6, -5
	s_add_i32 s7, s7, s1
	s_lshl_b32 s1, s6, 4
	s_bfe_u32 s6, s0, 0x40001
	s_or_b32 s13, s1, s6
	s_lshl_b32 s1, s7, 1
	s_and_b32 s0, s0, 1
	s_or_b32 s14, s1, s0

; DI int opaque_tid() { int t = threadIdx.x; asm volatile("" : "+v"(t)); return t; }
; DI void e1_chunk(const Params& p, int layer, int chunk) {
;   const int j = chunk & 7;
;   const size_t tok = (size_t)(chunk >> 3) * NTHR + opaque_tid();
;   if (j == 7) return;
;   u16* proj = (u16*)(p.ws + OFF_PROJ);
;   const int t = (int)(tok & 4095);
;   if (j < 6) {
; DI void run_phase(const Params& p, int ph, char* smem) {
;     ...
;       for (int c = bid; c < (T_TOK / NTHR) * 8; c += nb) e1_chunk(p, layer, c);
.LBB0_279:
	s_andn2_b64 vcc, exec, s[0:1]
	s_cbranch_vccnz .LBB0_309
	v_readlane_b32 s0, v254, 29
	v_readlane_b32 s1, v254, 30
	s_andn2_b64 vcc, exec, s[0:1]
	s_cbranch_vccnz .LBB0_288
	v_readlane_b32 s0, v255, 46
	s_lshl_b32 s0, s0, 6
	s_ashr_i32 s1, s0, 31
	s_lshl_b64 s[4:5], s[0:1], 2
	s_and_b32 s6, s28, 7
	s_mul_i32 s6, s6, 0xc0
	s_lshr_b32 s7, s28, 3
	s_add_i32 s6, s6, s7
	s_branch .LBB0_283
.LBB0_282:
	s_add_i32 s6, s6, 32
	v_readlane_b32 s7, v255, 9
	s_and_b32 s7, s7, 7
	s_mul_i32 s7, s7, 0xc0
	s_sub_i32 s7, s6, s7
	s_cmpk_gt_i32 s7, 0xbf
	s_cbranch_scc1 .LBB0_288

; DI void run_phase(const Params& p, int ph, char* smem) {
;     ...
;       for (int t = bid; t < MT * 2; t += nb) { const int nt = t & 1, mt = t >> 1; gemm_tile<EPI_UQ, false, true>(p, layer, (const u16*)(p.ws + OFF_PROJ) + 2048, DIN, wl + WT_UQ, 256, mt * 256, nt * 256, smem); }
.LBB0_288:
	v_readlane_b32 s0, v254, 31
	v_readlane_b32 s1, v254, 32
	s_andn2_b64 vcc, exec, s[0:1]
	s_cbranch_vccnz .LBB0_309
	v_readlane_b32 s0, v255, 48
	s_add_u32 s16, s0, 0x500000
	v_readlane_b32 s0, v255, 50
	s_addc_u32 s17, s0, 0
	s_and_b32 s20, s28, 7
	s_mul_i32 s20, s20, 0x60
	s_lshr_b32 s18, s28, 3
	s_add_i32 s20, s20, s18
	s_lshl_b32 s19, s20, 8
	s_lshl_b32 s18, s20, 7
	s_branch .LBB0_291
.LBB0_290:
	s_add_i32 s19, s19, 0x2000
	s_add_i32 s20, s20, 32
	s_add_i32 s18, s18, 0x1000
	v_readlane_b32 s0, v255, 9
	s_and_b32 s0, s0, 7
	s_mul_i32 s0, s0, 0x60
	s_sub_i32 s0, s20, s0
	s_cmpk_gt_i32 s0, 0x5f
	s_waitcnt lgkmcnt(0)
	s_barrier
	s_cbranch_scc1 .LBB0_297

; DI float fexp2(float x) { return __builtin_amdgcn_exp2f(x); }
; template <int EPI, bool ASCALE, bool ROWNORM>
; DI void gemm_tile(const Params& p, int layer, const u16* __restrict__ A, int lda, const u16* __restrict__ Wt, int K, int m0, int n0, char* smem) {
;     ...
;   if (ROWNORM) {
; #pragma unroll
;     for (int tm = 0; tm < TMW; ++tm) {
; #pragma unroll
;       for (int i = 0; i < 16; ++i) {
;         const float rs = rowscale[wms * 128 + 4 * h + 32 * tm + (i & 3) + 8 * (i >> 2)];
;         acc[tm][0][i] *= rs; acc[tm][1][i] *= rs;
;       }
;     }
;   }
;   if (EPI == EPI_SWIGLU) {
;     u16* dw = (u16*)(p.ws + OFF_ACT) + (size_t)mrow0 * DFF + (nwb >> 1);
;     const unsigned lo = (unsigned)(4 * h) * DFF + r;
; #pragma unroll
;     for (int tm = 0; tm < TMW; ++tm) {
; #pragma unroll
;       for (int i = 0; i < 16; ++i) {
;         const float g = acc[tm][0][i], u = acc[tm][1][i];
;         const float a = g * __builtin_amdgcn_rcpf(1.f + fexp2(-g * LOG2E)) * u;
;         dw[lo + (unsigned)((32 * tm + (i & 3) + 8 * (i >> 2)) * DFF)] = (u16)(pack2(a, 0.f) & 0xffff);
;       }
;       __builtin_amdgcn_sched_barrier(0);
;     }
;   } else {
; #pragma unroll
;     for (int tn = 0; tn < 2; ++tn) {
;       const int nb0 = nwb + 32 * tn;
;       if (EPI == EPI_RES) {
;         const float* xw = (layer == 0 ? (m0 < NPROMPT ? p.x_prompt + (size_t)mrow0 * DM : p.x_sample + (size_t)(mrow0 - NPROMPT) * DM) : p.out + (size_t)mrow0 * DM) + nb0;
;         float* ow = p.out + (size_t)mrow0 * DM + nb0;
;         const unsigned lo = (unsigned)(4 * h) * DM + r;
; #pragma unroll
;         for (int tm = 0; tm < TMW; ++tm) {
; #pragma unroll
;           for (int g4 = 0; g4 < 4; ++g4) {
;             float xv[4];
; #pragma unroll
;             for (int e = 0; e < 4; ++e) xv[e] = xw[lo + (unsigned)((32 * tm + 8 * g4 + e) * DM)];
; #pragma unroll
;             for (int e = 0; e < 4; ++e) ow[lo + (unsigned)((32 * tm + 8 * g4 + e) * DM)] = xv[e] + acc[tm][tn][4 * g4 + e];
;           }
;           __builtin_amdgcn_sched_barrier(0);
;         }
;       } else {
;         u16* dw; int ld; bool ok = true;
; DI void run_phase(const Params& p, int ph, char* smem) {
;     ...
;       for (int t = bid; t < MT * 2; t += nb) { const int nt = t & 1, mt = t >> 1; gemm_tile<EPI_UKV, false, true>(p, layer, (const u16*)(p.ws + OFF_PROJ) + 2304, DIN, wl + WT_UKV, 128, mt * 256, nt * 256, smem); }
.LBB0_297:
	v_readlane_b32 s0, v255, 48
	s_add_u32 s16, s0, 0x540000
	v_readlane_b32 s0, v255, 50
	s_addc_u32 s17, s0, 0
	s_and_b32 s20, s28, 7
	s_mul_i32 s20, s20, 0x60
	s_lshr_b32 s18, s28, 3
	s_add_i32 s20, s20, s18
	s_lshl_b32 s19, s20, 8
	s_lshl_b32 s18, s20, 7
	s_branch .LBB0_299
.LBB0_298:
	v_mul_f32_e32 v0, v2, v142
	v_mul_f32_e32 v2, v3, v143
	v_mul_f32_e32 v3, v4, v144
	v_mul_f32_e32 v4, v5, v145
	v_mul_f32_e32 v5, v6, v138
	v_mul_f32_e32 v6, v7, v139
	v_mul_f32_e32 v7, v8, v140
	v_mul_f32_e32 v8, v9, v141
	v_mul_f32_e32 v9, v10, v134
	v_mul_f32_e32 v10, v11, v135
	v_mul_f32_e32 v11, v12, v136
	v_mul_f32_e32 v12, v13, v137
	v_mul_f32_e32 v13, v14, v130
	v_mul_f32_e32 v14, v15, v131
	v_mul_f32_e32 v15, v16, v132
	v_mul_u32_u24_e32 v16, s0, v66
	v_or_b32_e32 v16, v16, v211
	v_cvt_pk_bf16_f32 v0, v0, s0
	v_lshlrev_b32_e32 v16, 1, v16
	global_store_short v16, v0, s[4:5]
	v_cvt_pk_bf16_f32 v0, v2, s0
	v_mad_u32_u24 v2, s0, v66, s0
	v_or_b32_e32 v16, v2, v211
	v_lshlrev_b32_e32 v16, 1, v16
	v_add_u32_e32 v2, s0, v2
	global_store_short v16, v0, s[4:5]
	v_cvt_pk_bf16_f32 v0, v3, s0
	v_or_b32_e32 v3, v2, v211
	v_lshlrev_b32_e32 v3, 1, v3
	v_add_u32_e32 v2, s0, v2
	global_store_short v3, v0, s[4:5]
	v_or_b32_e32 v3, v2, v211
	s_mul_i32 s1, s0, 5
	v_cvt_pk_bf16_f32 v0, v4, s0
	v_lshlrev_b32_e32 v3, 1, v3
	v_cvt_pk_bf16_f32 v4, v5, s0
	v_add_u32_e32 v5, s1, v2
	global_store_short v3, v0, s[4:5]
	v_or_b32_e32 v0, v5, v211
	v_add_u32_e32 v5, s0, v5
	v_lshl_add_u64 v[2:3], v[0:1], 1, s[4:5]
	v_or_b32_e32 v0, v5, v211
	v_add_u32_e32 v5, s0, v5
	global_store_short v[2:3], v4, off
	v_cvt_pk_bf16_f32 v4, v6, s0
	v_lshl_add_u64 v[2:3], v[0:1], 1, s[4:5]
	v_or_b32_e32 v0, v5, v211
	v_add_u32_e32 v5, s0, v5
	global_store_short v[2:3], v4, off
	v_cvt_pk_bf16_f32 v4, v7, s0
	v_lshl_add_u64 v[2:3], v[0:1], 1, s[4:5]
	v_or_b32_e32 v0, v5, v211
	v_add_u32_e32 v5, s1, v5
	global_store_short v[2:3], v4, off
	v_cvt_pk_bf16_f32 v4, v8, s0
	v_lshl_add_u64 v[2:3], v[0:1], 1, s[4:5]
	v_or_b32_e32 v0, v5, v211
	v_add_u32_e32 v5, s0, v5
	global_store_short v[2:3], v4, off
	v_cvt_pk_bf16_f32 v4, v9, s0
	v_lshl_add_u64 v[2:3], v[0:1], 1, s[4:5]
	v_or_b32_e32 v0, v5, v211
	v_add_u32_e32 v5, s0, v5
	global_store_short v[2:3], v4, off
	v_cvt_pk_bf16_f32 v4, v10, s0
	v_lshl_add_u64 v[2:3], v[0:1], 1, s[4:5]
	v_or_b32_e32 v0, v5, v211
	v_add_u32_e32 v5, s0, v5
	global_store_short v[2:3], v4, off
	v_cvt_pk_bf16_f32 v4, v11, s0
	v_lshl_add_u64 v[2:3], v[0:1], 1, s[4:5]
	v_or_b32_e32 v0, v5, v211
	v_add_u32_e32 v5, s1, v5
	global_store_short v[2:3], v4, off
	v_cvt_pk_bf16_f32 v4, v12, s0
	v_lshl_add_u64 v[2:3], v[0:1], 1, s[4:5]
	v_or_b32_e32 v0, v5, v211
	v_add_u32_e32 v5, s0, v5
	global_store_short v[2:3], v4, off
	v_cvt_pk_bf16_f32 v4, v13, s0
	v_lshl_add_u64 v[2:3], v[0:1], 1, s[4:5]
	v_or_b32_e32 v0, v5, v211
	v_add_u32_e32 v5, s0, v5
	global_store_short v[2:3], v4, off
	v_cvt_pk_bf16_f32 v4, v14, s0
	v_lshl_add_u64 v[2:3], v[0:1], 1, s[4:5]
	v_or_b32_e32 v0, v5, v211
	v_add_u32_e32 v5, s0, v5
	v_mul_f32_e32 v17, v17, v133
	global_store_short v[2:3], v4, off
	v_cvt_pk_bf16_f32 v4, v15, s0
	v_lshl_add_u64 v[2:3], v[0:1], 1, s[4:5]
	v_or_b32_e32 v0, v5, v211
	global_store_short v[2:3], v4, off
	v_cvt_pk_bf16_f32 v4, v17, s0
	v_lshl_add_u64 v[2:3], v[0:1], 1, s[4:5]
	v_mul_f32_e32 v65, v65, v181
	v_mul_f32_e32 v50, v50, v190
	v_mul_f32_e32 v51, v51, v191
	v_mul_f32_e32 v52, v52, v192
	v_mul_f32_e32 v53, v53, v193
	v_mul_f32_e32 v54, v54, v186
	v_mul_f32_e32 v55, v55, v187
	v_mul_f32_e32 v56, v56, v188
	v_mul_f32_e32 v57, v57, v189
	v_mul_f32_e32 v58, v58, v182
	v_mul_f32_e32 v59, v59, v183
	v_mul_f32_e32 v60, v60, v184
	v_mul_f32_e32 v61, v61, v185
	v_mul_f32_e32 v62, v62, v178
	v_mul_f32_e32 v63, v63, v179
	v_mul_f32_e32 v64, v64, v180
	v_mul_f32_e32 v49, v49, v165
	v_mul_f32_e32 v34, v34, v174
	v_mul_f32_e32 v35, v35, v175
	v_mul_f32_e32 v36, v36, v176
	v_mul_f32_e32 v37, v37, v177
	v_mul_f32_e32 v38, v38, v170
	v_mul_f32_e32 v39, v39, v171
	v_mul_f32_e32 v40, v40, v172
	v_mul_f32_e32 v41, v41, v173
	v_mul_f32_e32 v42, v42, v166
	v_mul_f32_e32 v43, v43, v167
	v_mul_f32_e32 v44, v44, v168
	v_mul_f32_e32 v45, v45, v169
	v_mul_f32_e32 v46, v46, v162
	v_mul_f32_e32 v47, v47, v163
	v_mul_f32_e32 v48, v48, v164
	v_mul_f32_e32 v33, v33, v149
	v_mul_f32_e32 v18, v18, v158
	v_mul_f32_e32 v19, v19, v159
	v_mul_f32_e32 v20, v20, v160
	v_mul_f32_e32 v21, v21, v161
	v_mul_f32_e32 v22, v22, v154
	v_mul_f32_e32 v23, v23, v155
	v_mul_f32_e32 v24, v24, v156
	v_mul_f32_e32 v25, v25, v157
	v_mul_f32_e32 v26, v26, v150
	v_mul_f32_e32 v27, v27, v151
	v_mul_f32_e32 v28, v28, v152
	v_mul_f32_e32 v29, v29, v153
	v_mul_f32_e32 v30, v30, v146
	v_mul_f32_e32 v31, v31, v147
	v_mul_f32_e32 v32, v32, v148
	global_store_short v[2:3], v4, off
	v_add_u32_e32 v5, s1, v5
	v_or_b32_e32 v0, v5, v211
	v_add_u32_e32 v5, s0, v5
	v_cvt_pk_bf16_f32 v4, v18, s0
	v_lshl_add_u64 v[2:3], v[0:1], 1, s[4:5]
	v_or_b32_e32 v0, v5, v211
	v_add_u32_e32 v5, s0, v5
	global_store_short v[2:3], v4, off
	v_cvt_pk_bf16_f32 v4, v19, s0
	v_lshl_add_u64 v[2:3], v[0:1], 1, s[4:5]
	v_or_b32_e32 v0, v5, v211
	v_add_u32_e32 v5, s0, v5
	global_store_short v[2:3], v4, off
	v_cvt_pk_bf16_f32 v4, v20, s0
	v_lshl_add_u64 v[2:3], v[0:1], 1, s[4:5]
	v_or_b32_e32 v0, v5, v211
	v_add_u32_e32 v5, s1, v5
	global_store_short v[2:3], v4, off
	v_cvt_pk_bf16_f32 v4, v21, s0
	v_lshl_add_u64 v[2:3], v[0:1], 1, s[4:5]
	v_or_b32_e32 v0, v5, v211
	v_add_u32_e32 v5, s0, v5
	global_store_short v[2:3], v4, off
	v_cvt_pk_bf16_f32 v4, v22, s0
	v_lshl_add_u64 v[2:3], v[0:1], 1, s[4:5]
	v_or_b32_e32 v0, v5, v211
	v_add_u32_e32 v5, s0, v5
; DI unsigned pack2(float a, float b) { f32x2 v = {a, b}; bf16v2 r = __builtin_convertvector(v, bf16v2); return __builtin_bit_cast(unsigned, r); }
; template <int EPI, bool ASCALE, bool ROWNORM>
; DI void gemm_tile(const Params& p, int layer, const u16* __restrict__ A, int lda, const u16* __restrict__ Wt, int K, int m0, int n0, char* smem) {
;     ...
;         const unsigned lo = (unsigned)(4 * h) * ld + r;
;         if (ok) {
; #pragma unroll
;           for (int tm = 0; tm < TMW; ++tm) {
; #pragma unroll
;             for (int i = 0; i < 16; ++i) dw[lo + (unsigned)((32 * tm + (i & 3) + 8 * (i >> 2)) * ld)] = (u16)(pack2(acc[tm][tn][i], 0.f) & 0xffff);
;             __builtin_amdgcn_sched_barrier(0);
;           }
	global_store_short v[2:3], v4, off
	v_cvt_pk_bf16_f32 v4, v23, s0
	v_lshl_add_u64 v[2:3], v[0:1], 1, s[4:5]
	v_or_b32_e32 v0, v5, v211
	v_add_u32_e32 v5, s0, v5
	global_store_short v[2:3], v4, off
	v_cvt_pk_bf16_f32 v4, v24, s0
	v_lshl_add_u64 v[2:3], v[0:1], 1, s[4:5]
	v_or_b32_e32 v0, v5, v211
	v_add_u32_e32 v5, s1, v5
	global_store_short v[2:3], v4, off
	v_cvt_pk_bf16_f32 v4, v25, s0
	v_lshl_add_u64 v[2:3], v[0:1], 1, s[4:5]
	v_or_b32_e32 v0, v5, v211
	v_add_u32_e32 v5, s0, v5
	global_store_short v[2:3], v4, off
	v_cvt_pk_bf16_f32 v4, v26, s0
	v_lshl_add_u64 v[2:3], v[0:1], 1, s[4:5]
	v_or_b32_e32 v0, v5, v211
	v_add_u32_e32 v5, s0, v5
	global_store_short v[2:3], v4, off
	v_cvt_pk_bf16_f32 v4, v27, s0
	v_lshl_add_u64 v[2:3], v[0:1], 1, s[4:5]
	v_or_b32_e32 v0, v5, v211
	v_add_u32_e32 v5, s0, v5
	global_store_short v[2:3], v4, off
	v_cvt_pk_bf16_f32 v4, v28, s0
	v_lshl_add_u64 v[2:3], v[0:1], 1, s[4:5]
	v_or_b32_e32 v0, v5, v211
	v_add_u32_e32 v5, s1, v5
	global_store_short v[2:3], v4, off
	v_cvt_pk_bf16_f32 v4, v29, s0
	v_lshl_add_u64 v[2:3], v[0:1], 1, s[4:5]
	v_or_b32_e32 v0, v5, v211
	v_add_u32_e32 v5, s0, v5
	global_store_short v[2:3], v4, off
	v_cvt_pk_bf16_f32 v4, v30, s0
	v_lshl_add_u64 v[2:3], v[0:1], 1, s[4:5]
	v_or_b32_e32 v0, v5, v211
	v_add_u32_e32 v5, s0, v5
	global_store_short v[2:3], v4, off
	v_cvt_pk_bf16_f32 v4, v31, s0
	v_lshl_add_u64 v[2:3], v[0:1], 1, s[4:5]
	v_or_b32_e32 v0, v5, v211
	v_add_u32_e32 v5, s0, v5
	global_store_short v[2:3], v4, off
	v_cvt_pk_bf16_f32 v4, v32, s0
	v_lshl_add_u64 v[2:3], v[0:1], 1, s[4:5]
	v_or_b32_e32 v0, v5, v211
	global_store_short v[2:3], v4, off
	v_cvt_pk_bf16_f32 v4, v33, s0
	v_lshl_add_u64 v[2:3], v[0:1], 1, s[4:5]
	global_store_short v[2:3], v4, off
	v_add_u32_e32 v5, s1, v5
	v_or_b32_e32 v0, v5, v211
	v_add_u32_e32 v5, s0, v5
	v_cvt_pk_bf16_f32 v4, v34, s0
	v_lshl_add_u64 v[2:3], v[0:1], 1, s[4:5]
	v_or_b32_e32 v0, v5, v211
	v_add_u32_e32 v5, s0, v5
	global_store_short v[2:3], v4, off
	v_cvt_pk_bf16_f32 v4, v35, s0
	v_lshl_add_u64 v[2:3], v[0:1], 1, s[4:5]
	v_or_b32_e32 v0, v5, v211
	v_add_u32_e32 v5, s0, v5
	global_store_short v[2:3], v4, off
	v_cvt_pk_bf16_f32 v4, v36, s0
	v_lshl_add_u64 v[2:3], v[0:1], 1, s[4:5]
	v_or_b32_e32 v0, v5, v211
	v_add_u32_e32 v5, s1, v5
	global_store_short v[2:3], v4, off
	v_cvt_pk_bf16_f32 v4, v37, s0
	v_lshl_add_u64 v[2:3], v[0:1], 1, s[4:5]
	v_or_b32_e32 v0, v5, v211
	v_add_u32_e32 v5, s0, v5
	global_store_short v[2:3], v4, off
	v_cvt_pk_bf16_f32 v4, v38, s0
	v_lshl_add_u64 v[2:3], v[0:1], 1, s[4:5]
	v_or_b32_e32 v0, v5, v211
	v_add_u32_e32 v5, s0, v5
	global_store_short v[2:3], v4, off
	v_cvt_pk_bf16_f32 v4, v39, s0
	v_lshl_add_u64 v[2:3], v[0:1], 1, s[4:5]
	v_or_b32_e32 v0, v5, v211
	v_add_u32_e32 v5, s0, v5
	global_store_short v[2:3], v4, off
	v_cvt_pk_bf16_f32 v4, v40, s0
	v_lshl_add_u64 v[2:3], v[0:1], 1, s[4:5]
	v_or_b32_e32 v0, v5, v211
	v_add_u32_e32 v5, s1, v5
	global_store_short v[2:3], v4, off
	v_cvt_pk_bf16_f32 v4, v41, s0
	v_lshl_add_u64 v[2:3], v[0:1], 1, s[4:5]
	v_or_b32_e32 v0, v5, v211
	v_add_u32_e32 v5, s0, v5
	global_store_short v[2:3], v4, off
	v_cvt_pk_bf16_f32 v4, v42, s0
	v_lshl_add_u64 v[2:3], v[0:1], 1, s[4:5]
	v_or_b32_e32 v0, v5, v211
	v_add_u32_e32 v5, s0, v5
	global_store_short v[2:3], v4, off
	v_cvt_pk_bf16_f32 v4, v43, s0
	v_lshl_add_u64 v[2:3], v[0:1], 1, s[4:5]
	v_or_b32_e32 v0, v5, v211
	v_add_u32_e32 v5, s0, v5
	global_store_short v[2:3], v4, off
	v_cvt_pk_bf16_f32 v4, v44, s0
	v_lshl_add_u64 v[2:3], v[0:1], 1, s[4:5]
	v_or_b32_e32 v0, v5, v211
	v_add_u32_e32 v5, s1, v5
	global_store_short v[2:3], v4, off
; DI unsigned pack2(float a, float b) { f32x2 v = {a, b}; bf16v2 r = __builtin_convertvector(v, bf16v2); return __builtin_bit_cast(unsigned, r); }
; template <int EPI, bool ASCALE, bool ROWNORM>
; DI void gemm_tile(const Params& p, int layer, const u16* __restrict__ A, int lda, const u16* __restrict__ Wt, int K, int m0, int n0, char* smem) {
;     ...
;         const unsigned lo = (unsigned)(4 * h) * ld + r;
;         if (ok) {
; #pragma unroll
;           for (int tm = 0; tm < TMW; ++tm) {
; #pragma unroll
;             for (int i = 0; i < 16; ++i) dw[lo + (unsigned)((32 * tm + (i & 3) + 8 * (i >> 2)) * ld)] = (u16)(pack2(acc[tm][tn][i], 0.f) & 0xffff);
;             __builtin_amdgcn_sched_barrier(0);
;           }
; DI void run_phase(const Params& p, int ph, char* smem) {
;     ...
;       for (int t = bid; t < MT * 2; t += nb) { const int nt = t & 1, mt = t >> 1; gemm_tile<EPI_UKV, false, true>(p, layer, (const u16*)(p.ws + OFF_PROJ) + 2304, DIN, wl + WT_UKV, 128, mt * 256, nt * 256, smem); }
	v_cvt_pk_bf16_f32 v4, v45, s0
	v_lshl_add_u64 v[2:3], v[0:1], 1, s[4:5]
	v_or_b32_e32 v0, v5, v211
	v_add_u32_e32 v5, s0, v5
	global_store_short v[2:3], v4, off
	v_cvt_pk_bf16_f32 v4, v46, s0
	v_lshl_add_u64 v[2:3], v[0:1], 1, s[4:5]
	v_or_b32_e32 v0, v5, v211
	v_add_u32_e32 v5, s0, v5
	global_store_short v[2:3], v4, off
	v_cvt_pk_bf16_f32 v4, v47, s0
	v_lshl_add_u64 v[2:3], v[0:1], 1, s[4:5]
	v_or_b32_e32 v0, v5, v211
	v_add_u32_e32 v5, s0, v5
	global_store_short v[2:3], v4, off
	v_cvt_pk_bf16_f32 v4, v48, s0
	v_lshl_add_u64 v[2:3], v[0:1], 1, s[4:5]
	v_or_b32_e32 v0, v5, v211
	global_store_short v[2:3], v4, off
	v_cvt_pk_bf16_f32 v4, v49, s0
	v_lshl_add_u64 v[2:3], v[0:1], 1, s[4:5]
	global_store_short v[2:3], v4, off
	v_add_u32_e32 v5, s1, v5
	v_or_b32_e32 v0, v5, v211
	v_add_u32_e32 v5, s0, v5
	v_cvt_pk_bf16_f32 v4, v50, s0
	v_lshl_add_u64 v[2:3], v[0:1], 1, s[4:5]
	v_or_b32_e32 v0, v5, v211
	v_add_u32_e32 v5, s0, v5
	global_store_short v[2:3], v4, off
	v_cvt_pk_bf16_f32 v4, v51, s0
	v_lshl_add_u64 v[2:3], v[0:1], 1, s[4:5]
	v_or_b32_e32 v0, v5, v211
	v_add_u32_e32 v5, s0, v5
	global_store_short v[2:3], v4, off
	v_cvt_pk_bf16_f32 v4, v52, s0
	v_lshl_add_u64 v[2:3], v[0:1], 1, s[4:5]
	v_or_b32_e32 v0, v5, v211
	v_add_u32_e32 v5, s1, v5
	global_store_short v[2:3], v4, off
	v_cvt_pk_bf16_f32 v4, v53, s0
	v_lshl_add_u64 v[2:3], v[0:1], 1, s[4:5]
	v_or_b32_e32 v0, v5, v211
	v_add_u32_e32 v5, s0, v5
	global_store_short v[2:3], v4, off
	v_cvt_pk_bf16_f32 v4, v54, s0
	v_lshl_add_u64 v[2:3], v[0:1], 1, s[4:5]
	v_or_b32_e32 v0, v5, v211
	v_add_u32_e32 v5, s0, v5
	global_store_short v[2:3], v4, off
	v_cvt_pk_bf16_f32 v4, v55, s0
	v_lshl_add_u64 v[2:3], v[0:1], 1, s[4:5]
	v_or_b32_e32 v0, v5, v211
	v_add_u32_e32 v5, s0, v5
	global_store_short v[2:3], v4, off
	v_cvt_pk_bf16_f32 v4, v56, s0
	v_lshl_add_u64 v[2:3], v[0:1], 1, s[4:5]
	v_or_b32_e32 v0, v5, v211
	v_add_u32_e32 v5, s1, v5
	global_store_short v[2:3], v4, off
	v_cvt_pk_bf16_f32 v4, v57, s0
	v_lshl_add_u64 v[2:3], v[0:1], 1, s[4:5]
	v_or_b32_e32 v0, v5, v211
	v_add_u32_e32 v5, s0, v5
	global_store_short v[2:3], v4, off
	v_cvt_pk_bf16_f32 v4, v58, s0
	v_lshl_add_u64 v[2:3], v[0:1], 1, s[4:5]
	v_or_b32_e32 v0, v5, v211
	v_add_u32_e32 v5, s0, v5
	global_store_short v[2:3], v4, off
	v_cvt_pk_bf16_f32 v4, v59, s0
	v_lshl_add_u64 v[2:3], v[0:1], 1, s[4:5]
	v_or_b32_e32 v0, v5, v211
	v_add_u32_e32 v5, s0, v5
	global_store_short v[2:3], v4, off
	v_cvt_pk_bf16_f32 v4, v60, s0
	v_lshl_add_u64 v[2:3], v[0:1], 1, s[4:5]
	v_or_b32_e32 v0, v5, v211
	v_add_u32_e32 v5, s1, v5
	global_store_short v[2:3], v4, off
	v_cvt_pk_bf16_f32 v4, v61, s0
	v_lshl_add_u64 v[2:3], v[0:1], 1, s[4:5]
	v_or_b32_e32 v0, v5, v211
	v_add_u32_e32 v5, s0, v5
	global_store_short v[2:3], v4, off
	v_cvt_pk_bf16_f32 v4, v62, s0
	v_lshl_add_u64 v[2:3], v[0:1], 1, s[4:5]
	v_or_b32_e32 v0, v5, v211
	v_add_u32_e32 v5, s0, v5
	global_store_short v[2:3], v4, off
	v_cvt_pk_bf16_f32 v4, v63, s0
	v_lshl_add_u64 v[2:3], v[0:1], 1, s[4:5]
	v_or_b32_e32 v0, v5, v211
	global_store_short v[2:3], v4, off
	v_lshl_add_u64 v[2:3], v[0:1], 1, s[4:5]
	v_add_u32_e32 v0, s0, v5
	v_cvt_pk_bf16_f32 v4, v64, s0
	v_or_b32_e32 v0, v0, v211
	global_store_short v[2:3], v4, off
	v_cvt_pk_bf16_f32 v4, v65, s0
	v_lshl_add_u64 v[2:3], v[0:1], 1, s[4:5]
	global_store_short v[2:3], v4, off
	s_add_i32 s19, s19, 0x2000
	s_add_i32 s20, s20, 32
	s_add_i32 s18, s18, 0x1000
	v_readlane_b32 s0, v255, 9
	s_and_b32 s0, s0, 7
	s_mul_i32 s0, s0, 0x60
	s_sub_i32 s0, s20, s0
	s_cmpk_gt_i32 s0, 0x5f
	s_waitcnt vmcnt(63) expcnt(7) lgkmcnt(15)
	s_barrier
	s_cbranch_scc1 .LBB0_309
